# grid barrier: all workgroups poll the cross-XCD arrival counter directly (no TOPGEN hop), leaders add without waiting for the return
# speedup vs baseline: 1.0016x; 1.0016x over previous
.LBB0_188:
	s_or_b64 exec, exec, s[10:11]
	v_cvt_f32_u32_e32 v7, v4
	s_waitcnt vmcnt(0)
	v_readfirstlane_b32 s10, v5
	v_sub_u32_e32 v5, 0, v4
	v_rcp_iflag_f32_e32 v7, v7
	v_add_u32_e32 v8, s10, v1
	v_mul_f32_e32 v7, 0x4f7ffffe, v7
	v_cvt_u32_f32_e32 v7, v7
	v_mul_lo_u32 v1, v5, v7
	v_mul_hi_u32 v1, v7, v1
	v_add_u32_e32 v1, v7, v1
	v_mul_hi_u32 v1, v8, v1
	v_mul_lo_u32 v5, v1, v4
	v_sub_u32_e32 v5, v8, v5
	v_add_u32_e32 v7, 1, v1
	v_cmp_ge_u32_e32 vcc, v5, v4
	s_nop 1
	v_cndmask_b32_e32 v1, v1, v7, vcc
	v_sub_u32_e32 v7, v5, v4
	v_cndmask_b32_e32 v5, v5, v7, vcc
	v_add_u32_e32 v7, 1, v1
	v_cmp_ge_u32_e32 vcc, v5, v4
	v_add_u32_e32 v5, 1, v8
	s_nop 0
	v_cndmask_b32_e32 v1, v1, v7, vcc
	v_mul_lo_u32 v7, v4, v1
	v_add_u32_e32 v4, v7, v4
	v_cmp_ne_u32_e32 vcc, v5, v4
	v_add_u32_e32 v8, 1, v1
	v_readlane_b32 s12, v252, 39
	v_readlane_b32 s13, v252, 40
	s_waitcnt lgkmcnt(0)
	v_mul_lo_u32 v7, v8, v2
	v_mov_b32_e32 v5, 1
	s_mov_b32 s25, 0
	s_nop 4
	s_cbranch_vccnz .Lxb_poll_1
	buffer_wbl2 sc1
	s_waitcnt vmcnt(0)
	global_atomic_add v3, v5, s[12:13]
.Lxb_poll_1:
	global_load_dword v2, v3, s[12:13] sc1
	s_waitcnt vmcnt(0)
	v_cmp_ge_u32_e32 vcc, v2, v7
	s_cbranch_vccnz .Lxb_done_1
	s_sleep 1
	s_add_i32 s25, s25, 1
	s_and_b32 s20, s25, 0xff
	s_cmp_lg_u32 s20, 0
	s_cbranch_scc1 .Lxb_poll_1
	global_load_dword v2, v3, s[88:89] sc1
	s_waitcnt vmcnt(0)
	v_cmp_ne_u32_e32 vcc, 0, v2
	s_cbranch_vccnz .Lxb_done_1
	s_cmp_lt_u32 s25, 0x40001
	s_cbranch_scc1 .Lxb_poll_1
	global_atomic_add v3, v5, s[88:89]
.Lxb_done_1:
	s_waitcnt vmcnt(0)
	buffer_inv sc1
	s_waitcnt vmcnt(0)

.LBB0_296:
	s_or_b64 exec, exec, s[12:13]
	v_cvt_f32_u32_e32 v7, v4
	s_waitcnt vmcnt(0)
	v_readfirstlane_b32 s12, v5
	v_sub_u32_e32 v5, 0, v4
	v_rcp_iflag_f32_e32 v7, v7
	v_add_u32_e32 v8, s12, v1
	v_mul_f32_e32 v7, 0x4f7ffffe, v7
	v_cvt_u32_f32_e32 v7, v7
	v_mul_lo_u32 v1, v5, v7
	v_mul_hi_u32 v1, v7, v1
	v_add_u32_e32 v1, v7, v1
	v_mul_hi_u32 v1, v8, v1
	v_mul_lo_u32 v5, v1, v4
	v_sub_u32_e32 v5, v8, v5
	v_add_u32_e32 v7, 1, v1
	v_cmp_ge_u32_e32 vcc, v5, v4
	s_nop 1
	v_cndmask_b32_e32 v1, v1, v7, vcc
	v_sub_u32_e32 v7, v5, v4
	v_cndmask_b32_e32 v5, v5, v7, vcc
	v_add_u32_e32 v7, 1, v1
	v_cmp_ge_u32_e32 vcc, v5, v4
	v_add_u32_e32 v5, 1, v8
	s_nop 0
	v_cndmask_b32_e32 v1, v1, v7, vcc
	v_mul_lo_u32 v7, v4, v1
	v_add_u32_e32 v4, v7, v4
	v_cmp_ne_u32_e32 vcc, v5, v4
	v_add_u32_e32 v8, 1, v1
	v_readlane_b32 s14, v252, 39
	v_readlane_b32 s15, v252, 40
	s_waitcnt lgkmcnt(0)
	v_mul_lo_u32 v7, v8, v2
	v_mov_b32_e32 v5, 1
	s_mov_b32 s26, 0
	s_nop 4
	s_cbranch_vccnz .Lxb_poll_2
	buffer_wbl2 sc1
	s_waitcnt vmcnt(0)
	global_atomic_add v3, v5, s[14:15]
.Lxb_poll_2:
	global_load_dword v2, v3, s[14:15] sc1
	s_waitcnt vmcnt(0)
	v_cmp_ge_u32_e32 vcc, v2, v7
	s_cbranch_vccnz .Lxb_done_2
	s_sleep 1
	s_add_i32 s26, s26, 1
	s_and_b32 s22, s26, 0xff
	s_cmp_lg_u32 s22, 0
	s_cbranch_scc1 .Lxb_poll_2
	global_load_dword v2, v3, s[88:89] sc1
	s_waitcnt vmcnt(0)
	v_cmp_ne_u32_e32 vcc, 0, v2
	s_cbranch_vccnz .Lxb_done_2
	s_cmp_lt_u32 s26, 0x40001
	s_cbranch_scc1 .Lxb_poll_2
	global_atomic_add v3, v5, s[88:89]
.Lxb_done_2:
	s_waitcnt vmcnt(0)
	buffer_inv sc1
	s_waitcnt vmcnt(0)
	v_readlane_b32 s26, v254, 40
	v_readlane_b32 s27, v254, 41
	s_mov_b32 s24, 0x32900000

.LBB0_940:
	s_or_b64 exec, exec, s[8:9]
	v_cvt_f32_u32_e32 v7, v4
	s_waitcnt vmcnt(0)
	v_readfirstlane_b32 s8, v5
	v_sub_u32_e32 v5, 0, v4
	v_rcp_iflag_f32_e32 v7, v7
	v_add_u32_e32 v8, s8, v1
	v_mul_f32_e32 v7, 0x4f7ffffe, v7
	v_cvt_u32_f32_e32 v7, v7
	v_mul_lo_u32 v1, v5, v7
	v_mul_hi_u32 v1, v7, v1
	v_add_u32_e32 v1, v7, v1
	v_mul_hi_u32 v1, v8, v1
	v_mul_lo_u32 v5, v1, v4
	v_sub_u32_e32 v5, v8, v5
	v_add_u32_e32 v7, 1, v1
	v_cmp_ge_u32_e32 vcc, v5, v4
	s_nop 1
	v_cndmask_b32_e32 v1, v1, v7, vcc
	v_sub_u32_e32 v7, v5, v4
	v_cndmask_b32_e32 v5, v5, v7, vcc
	v_add_u32_e32 v7, 1, v1
	v_cmp_ge_u32_e32 vcc, v5, v4
	v_add_u32_e32 v5, 1, v8
	s_nop 0
	v_cndmask_b32_e32 v1, v1, v7, vcc
	v_mul_lo_u32 v7, v4, v1
	v_add_u32_e32 v4, v7, v4
	v_cmp_ne_u32_e32 vcc, v5, v4
	v_add_u32_e32 v8, 1, v1
	v_readlane_b32 s10, v252, 39
	v_readlane_b32 s11, v252, 40
	s_waitcnt lgkmcnt(0)
	v_mul_lo_u32 v7, v8, v2
	v_mov_b32_e32 v5, 1
	s_mov_b32 s22, 0
	s_nop 4
	s_cbranch_vccnz .Lxb_poll_6
	buffer_wbl2 sc1
	s_waitcnt vmcnt(0)
	global_atomic_add v3, v5, s[10:11]
.Lxb_poll_6:
	global_load_dword v2, v3, s[10:11] sc1
	s_waitcnt vmcnt(0)
	v_cmp_ge_u32_e32 vcc, v2, v7
	s_cbranch_vccnz .Lxb_done_6
	s_sleep 1
	s_add_i32 s22, s22, 1
	s_and_b32 s18, s22, 0xff
	s_cmp_lg_u32 s18, 0
	s_cbranch_scc1 .Lxb_poll_6
	global_load_dword v2, v3, s[88:89] sc1
	s_waitcnt vmcnt(0)
	v_cmp_ne_u32_e32 vcc, 0, v2
	s_cbranch_vccnz .Lxb_done_6
	s_cmp_lt_u32 s22, 0x40001
	s_cbranch_scc1 .Lxb_poll_6
	global_atomic_add v3, v5, s[88:89]

.LBB0_1508:
	s_or_b64 exec, exec, s[10:11]
	v_cvt_f32_u32_e32 v7, v4
	s_waitcnt vmcnt(0)
	v_readfirstlane_b32 s10, v5
	v_sub_u32_e32 v5, 0, v4
	v_rcp_iflag_f32_e32 v7, v7
	v_add_u32_e32 v8, s10, v1
	v_mul_f32_e32 v7, 0x4f7ffffe, v7
	v_cvt_u32_f32_e32 v7, v7
	v_mul_lo_u32 v1, v5, v7
	v_mul_hi_u32 v1, v7, v1
	v_add_u32_e32 v1, v7, v1
	v_mul_hi_u32 v1, v8, v1
	v_mul_lo_u32 v5, v1, v4
	v_sub_u32_e32 v5, v8, v5
	v_add_u32_e32 v7, 1, v1
	v_cmp_ge_u32_e32 vcc, v5, v4
	s_nop 1
	v_cndmask_b32_e32 v1, v1, v7, vcc
	v_sub_u32_e32 v7, v5, v4
	v_cndmask_b32_e32 v5, v5, v7, vcc
	v_add_u32_e32 v7, 1, v1
	v_cmp_ge_u32_e32 vcc, v5, v4
	v_add_u32_e32 v5, 1, v8
	s_nop 0
	v_cndmask_b32_e32 v1, v1, v7, vcc
	v_mul_lo_u32 v7, v4, v1
	v_add_u32_e32 v4, v7, v4
	v_cmp_ne_u32_e32 vcc, v5, v4
	v_add_u32_e32 v8, 1, v1
	v_readlane_b32 s12, v252, 39
	v_readlane_b32 s13, v252, 40
	s_waitcnt lgkmcnt(0)
	v_mul_lo_u32 v7, v8, v2
	v_mov_b32_e32 v5, 1
	s_mov_b32 s24, 0
	s_nop 4
	s_cbranch_vccnz .Lxb_poll_10
	buffer_wbl2 sc1
	s_waitcnt vmcnt(0)
	global_atomic_add v3, v5, s[12:13]
.Lxb_poll_10:
	global_load_dword v2, v3, s[12:13] sc1
	s_waitcnt vmcnt(0)
	v_cmp_ge_u32_e32 vcc, v2, v7
	s_cbranch_vccnz .Lxb_done_10
	s_sleep 1
	s_add_i32 s24, s24, 1
	s_and_b32 s20, s24, 0xff
	s_cmp_lg_u32 s20, 0
	s_cbranch_scc1 .Lxb_poll_10
	global_load_dword v2, v3, s[88:89] sc1
	s_waitcnt vmcnt(0)
	v_cmp_ne_u32_e32 vcc, 0, v2
	s_cbranch_vccnz .Lxb_done_10
	s_cmp_lt_u32 s24, 0x40001
	s_cbranch_scc1 .Lxb_poll_10
	global_atomic_add v3, v5, s[88:89]
.Lxb_done_10:
	s_waitcnt vmcnt(0)
	buffer_inv sc1
	s_waitcnt vmcnt(0)
	s_mov_b32 s24, 0x32900000
	s_mov_b64 s[12:13], 0
	s_getpc_b64 s[98:99]
